# v27 + GEMM K-loops: hipcc's wave-uniform next-stage test shortened to s_add/s_cmp/s_cbranch (10 sites)
# speedup vs baseline: 1.0132x; 1.0046x over previous
.LBB0_130:
	v_add_u32_e32 v164, v168, v189
	v_add_u32_e32 v169, v146, v189
	s_waitcnt lgkmcnt(2)
	v_mfma_f32_32x32x16_bf16 v[0:15], v[128:131], v[132:135], v[0:15]
	ds_read_b128 v[156:159], v164
	s_add_u32 s0, s0, 0x80
	s_addc_u32 s1, s1, 0
	s_add_i32 s47, s47, 1
	s_cmpk_lg_i32 s0, 0x800
	s_mov_b32 s48, s52
	v_mfma_f32_32x32x16_bf16 v[16:31], v[152:155], v[132:135], v[16:31]
	ds_read_b128 v[132:135], v164 offset:4096
	s_waitcnt lgkmcnt(4)
	v_mfma_f32_32x32x16_bf16 v[32:47], v[128:131], v[136:139], v[32:47]
	ds_read_b128 v[160:163], v164 offset:8192
	v_mfma_f32_32x32x16_bf16 v[48:63], v[152:155], v[136:139], v[48:63]
	ds_read_b128 v[136:139], v164 offset:12288
	s_waitcnt lgkmcnt(5)
	v_mfma_f32_32x32x16_bf16 v[64:79], v[128:131], v[140:143], v[64:79]
	ds_read_b128 v[164:167], v169 offset:32768
	v_mfma_f32_32x32x16_bf16 v[80:95], v[152:155], v[140:143], v[80:95]
	ds_read_b128 v[140:143], v169 offset:36864
	v_add_u32_e32 v169, v168, v190
	s_waitcnt lgkmcnt(6)
	v_mfma_f32_32x32x16_bf16 v[96:111], v[128:131], v[148:151], v[96:111]
	v_mfma_f32_32x32x16_bf16 v[112:127], v[152:155], v[148:151], v[112:127]
	s_waitcnt lgkmcnt(1)
	v_mfma_f32_32x32x16_bf16 v[0:15], v[164:167], v[156:159], v[0:15]
	ds_read_b128 v[128:131], v169
	s_waitcnt lgkmcnt(1)
	v_mfma_f32_32x32x16_bf16 v[16:31], v[140:143], v[156:159], v[16:31]
	ds_read_b128 v[148:151], v169 offset:4096
	v_mfma_f32_32x32x16_bf16 v[32:47], v[164:167], v[132:135], v[32:47]
	ds_read_b128 v[152:155], v169 offset:8192
	v_mfma_f32_32x32x16_bf16 v[48:63], v[140:143], v[132:135], v[48:63]
	ds_read_b128 v[132:135], v169 offset:12288
	v_add_u32_e32 v169, v146, v190
	v_add_u32_e32 v146, v146, v191
	v_mfma_f32_32x32x16_bf16 v[64:79], v[164:167], v[160:163], v[64:79]
	ds_read_b128 v[156:159], v169 offset:32768
	v_mfma_f32_32x32x16_bf16 v[80:95], v[140:143], v[160:163], v[80:95]
	ds_read_b128 v[160:163], v169 offset:36864
	v_mfma_f32_32x32x16_bf16 v[96:111], v[164:167], v[136:139], v[96:111]
	v_add_u32_e32 v164, v168, v191
	v_mfma_f32_32x32x16_bf16 v[112:127], v[140:143], v[136:139], v[112:127]
	s_waitcnt lgkmcnt(1)
	v_mfma_f32_32x32x16_bf16 v[0:15], v[156:159], v[128:131], v[0:15]
	ds_read_b128 v[136:139], v164
	s_waitcnt lgkmcnt(1)
	v_mfma_f32_32x32x16_bf16 v[16:31], v[160:163], v[128:131], v[16:31]
	ds_read_b128 v[128:131], v164 offset:4096
	v_mfma_f32_32x32x16_bf16 v[32:47], v[156:159], v[148:151], v[32:47]
	ds_read_b128 v[140:143], v164 offset:8192
	v_mfma_f32_32x32x16_bf16 v[48:63], v[160:163], v[148:151], v[48:63]
	ds_read_b128 v[148:151], v164 offset:12288
	v_mfma_f32_32x32x16_bf16 v[64:79], v[156:159], v[152:155], v[64:79]
	ds_read_b128 v[164:167], v146 offset:32768
	v_mfma_f32_32x32x16_bf16 v[80:95], v[160:163], v[152:155], v[80:95]
	ds_read_b128 v[152:155], v146 offset:36864
	v_mfma_f32_32x32x16_bf16 v[96:111], v[156:159], v[132:135], v[96:111]
	v_mfma_f32_32x32x16_bf16 v[112:127], v[160:163], v[132:135], v[112:127]
	s_waitcnt lgkmcnt(0)
	s_cbranch_scc0 .Lxt_L0
	s_waitcnt vmcnt(0)
	s_barrier
	s_and_b32 s4, s48, 0x10000
	v_or_b32_e32 v146, s4, v187
	v_add_u32_e32 v194, v146, v188
	v_add_u32_e32 v168, s4, v186
	v_add_u32_e32 v195, v168, v188
	ds_read_b128 v[132:135], v195
	v_mfma_f32_32x32x16_bf16 v[16:31], v[152:155], v[136:139], v[16:31]
	v_mfma_f32_32x32x16_bf16 v[48:63], v[152:155], v[128:131], v[48:63]
	v_mfma_f32_32x32x16_bf16 v[80:95], v[152:155], v[140:143], v[80:95]
	v_mfma_f32_32x32x16_bf16 v[112:127], v[152:155], v[148:151], v[112:127]
	ds_read_b128 v[152:155], v194 offset:36864
	v_mfma_f32_32x32x16_bf16 v[0:15], v[164:167], v[136:139], v[0:15]
	ds_read_b128 v[136:139], v195 offset:4096
	v_mfma_f32_32x32x16_bf16 v[32:47], v[164:167], v[128:131], v[32:47]
	ds_read_b128 v[128:131], v194 offset:32768
	v_mfma_f32_32x32x16_bf16 v[64:79], v[164:167], v[140:143], v[64:79]
	ds_read_b128 v[140:143], v195 offset:8192
	v_mfma_f32_32x32x16_bf16 v[96:111], v[164:167], v[148:151], v[96:111]
	ds_read_b128 v[148:151], v195 offset:12288
	s_add_i32 s52, s48, 0x10000
	s_cmp_lt_u32 s47, 15
	s_cbranch_scc0 .LBB0_130
	s_and_b32 s4, s52, 0x10000
	s_add_i32 s53, s4, s26
	s_add_i32 s54, s53, 0x8000
	s_add_u32 s82, s0, s81
	s_addk_i32 s82, 0x80
	s_and_b32 s82, s82, 0x7ff
	s_mov_b32 s83, 0
	s_add_u32 s4, s45, s82
	s_addc_u32 s5, s46, s83
	s_mov_b32 m0, s53
	global_load_lds_dwordx4 v145, s[4:5]
	s_add_u32 s4, s43, s82
	s_addc_u32 s5, s44, s83
	s_add_i32 s55, s53, 0x400
	s_mov_b32 m0, s55
	global_load_lds_dwordx4 v185, s[4:5]
	s_add_u32 s4, s40, s82
	s_addc_u32 s5, s42, s83
	s_add_i32 s55, s53, 0x800
	s_mov_b32 m0, s55
	global_load_lds_dwordx4 v145, s[4:5]
	s_add_u32 s4, s37, s82
	s_addc_u32 s5, s39, s83
	s_add_i32 s55, s53, 0xc00
	s_mov_b32 m0, s55
	global_load_lds_dwordx4 v185, s[4:5]
	s_add_u32 s4, s35, s82
	s_addc_u32 s5, s36, s83
	s_mov_b32 m0, s54
	global_load_lds_dwordx4 v145, s[4:5]
	s_add_u32 s4, s31, s82
	s_addc_u32 s5, s34, s83
	s_add_i32 s54, s53, 0x8400
	s_mov_b32 m0, s54
	global_load_lds_dwordx4 v185, s[4:5]
	s_add_u32 s4, s29, s82
	s_addc_u32 s5, s30, s83
	s_add_i32 s54, s53, 0x8800
	s_mov_b32 m0, s54
	global_load_lds_dwordx4 v145, s[4:5]
	s_add_u32 s4, s27, s82
	s_addc_u32 s5, s28, s83
	s_add_i32 s53, s53, 0x8c00
	s_mov_b32 m0, s53
	global_load_lds_dwordx4 v185, s[4:5]
	s_branch .LBB0_130

.Lkin_L0:
	s_and_b32 s4, s48, 0x10000
	v_or_b32_e32 v146, s4, v187
	v_add_u32_e32 v194, v146, v188
	v_add_u32_e32 v168, s4, v186
	v_add_u32_e32 v195, v168, v188
	ds_read_b128 v[132:135], v195
	ds_read_b128 v[152:155], v194 offset:36864
	ds_read_b128 v[136:139], v195 offset:4096
	ds_read_b128 v[128:131], v194 offset:32768
	ds_read_b128 v[140:143], v195 offset:8192
	ds_read_b128 v[148:151], v195 offset:12288
	s_add_i32 s52, s48, 0x10000
	s_cmp_lt_u32 s47, 15
	s_cbranch_scc0 .LBB0_130
	s_and_b32 s4, s52, 0x10000
	s_add_i32 s53, s4, s26
	s_add_i32 s54, s53, 0x8000
	s_add_u32 s82, s0, s81
	s_addk_i32 s82, 0x80
	s_and_b32 s82, s82, 0x7ff
	s_mov_b32 s83, 0
	s_add_u32 s4, s45, s82
	s_addc_u32 s5, s46, s83
	s_mov_b32 m0, s53
	global_load_lds_dwordx4 v145, s[4:5]
	s_add_u32 s4, s43, s82
	s_addc_u32 s5, s44, s83
	s_add_i32 s55, s53, 0x400
	s_mov_b32 m0, s55
	global_load_lds_dwordx4 v185, s[4:5]
	s_add_u32 s4, s40, s82
	s_addc_u32 s5, s42, s83
	s_add_i32 s55, s53, 0x800
	s_mov_b32 m0, s55
	global_load_lds_dwordx4 v145, s[4:5]
	s_add_u32 s4, s37, s82
	s_addc_u32 s5, s39, s83
	s_add_i32 s55, s53, 0xc00
	s_mov_b32 m0, s55
	global_load_lds_dwordx4 v185, s[4:5]
	s_add_u32 s4, s35, s82
	s_addc_u32 s5, s36, s83
	s_mov_b32 m0, s54
	global_load_lds_dwordx4 v145, s[4:5]
	s_add_u32 s4, s31, s82
	s_addc_u32 s5, s34, s83
	s_add_i32 s54, s53, 0x8400
	s_mov_b32 m0, s54
	global_load_lds_dwordx4 v185, s[4:5]
	s_add_u32 s4, s29, s82
	s_addc_u32 s5, s30, s83
	s_add_i32 s54, s53, 0x8800
	s_mov_b32 m0, s54
	global_load_lds_dwordx4 v145, s[4:5]
	s_add_u32 s4, s27, s82
	s_addc_u32 s5, s28, s83
	s_add_i32 s53, s53, 0x8c00
	s_mov_b32 m0, s53
	global_load_lds_dwordx4 v185, s[4:5]
	s_branch .LBB0_130

.LBB0_313:
	s_waitcnt vmcnt(0)
	s_barrier
	s_and_b32 s22, s59, 0x10000
	v_or_b32_e32 v128, s22, v152
	v_add_u32_e32 v157, v128, v153
	ds_read_b128 v[130:133], v157 offset:32768
	ds_read_b128 v[162:165], v157 offset:36864
	v_add_u32_e32 v180, s22, v151
	v_add_u32_e32 v158, v180, v153
	ds_read_b128 v[134:137], v158
	ds_read_b128 v[138:141], v158 offset:4096
	ds_read_b128 v[142:145], v158 offset:8192
	v_add_u32_e32 v157, v180, v154
	ds_read_b128 v[158:161], v158 offset:12288
	s_add_i32 s60, s59, 0x10000
	s_cmp_lt_u32 s58, 7
	s_cbranch_scc0 .LBB0_312
	s_and_b32 s22, s60, 0x10000
	s_add_i32 s61, s22, s25
	s_add_i32 s62, s61, 0x8000
	s_add_u32 s22, s56, s18
	s_addc_u32 s23, s57, s19
	s_mov_b32 m0, s61
	global_load_lds_dwordx4 v147, s[22:23]
	s_add_u32 s22, s54, s18
	s_addc_u32 s23, s55, s19
	s_add_i32 s63, s61, 0x400
	s_mov_b32 m0, s63
	global_load_lds_dwordx4 v148, s[22:23]
	s_add_u32 s22, s52, s18
	s_addc_u32 s23, s53, s19
	s_add_i32 s63, s61, 0x800
	s_mov_b32 m0, s63
	global_load_lds_dwordx4 v147, s[22:23]
	s_add_u32 s22, s50, s18
	s_addc_u32 s23, s51, s19
	s_add_i32 s63, s61, 0xc00
	s_mov_b32 m0, s63
	global_load_lds_dwordx4 v148, s[22:23]
	s_add_u32 s22, s48, s18
	s_addc_u32 s23, s49, s19
	s_mov_b32 m0, s62
	global_load_lds_dwordx4 v149, s[22:23]
	s_add_u32 s22, s46, s18
	s_addc_u32 s23, s47, s19
	s_add_i32 s62, s61, 0x8400
	s_mov_b32 m0, s62
	global_load_lds_dwordx4 v150, s[22:23]
	s_add_u32 s22, s44, s18
	s_addc_u32 s23, s45, s19
	s_add_i32 s62, s61, 0x8800
	s_mov_b32 m0, s62
	global_load_lds_dwordx4 v149, s[22:23]
	s_add_u32 s22, s41, s18
	s_addc_u32 s23, s42, s19
	s_add_i32 s61, s61, 0x8c00
	s_mov_b32 m0, s61
	global_load_lds_dwordx4 v150, s[22:23]
	s_branch .LBB0_312

.LBB0_327:
	s_waitcnt vmcnt(0)
	s_barrier
	s_and_b32 s22, s59, 0x10000
	v_or_b32_e32 v128, s22, v152
	v_add_u32_e32 v157, v128, v153
	ds_read_b128 v[130:133], v157 offset:32768
	ds_read_b128 v[162:165], v157 offset:36864
	v_add_u32_e32 v180, s22, v151
	v_add_u32_e32 v158, v180, v153
	ds_read_b128 v[134:137], v158
	ds_read_b128 v[138:141], v158 offset:4096
	ds_read_b128 v[142:145], v158 offset:8192
	v_add_u32_e32 v157, v180, v154
	ds_read_b128 v[158:161], v158 offset:12288
	s_add_i32 s60, s59, 0x10000
	s_cmp_lt_u32 s58, 7
	s_cbranch_scc0 .LBB0_326
	s_and_b32 s22, s60, 0x10000
	s_add_i32 s61, s22, s24
	s_add_i32 s62, s61, 0x8000
	s_add_u32 s22, s56, s20
	s_addc_u32 s23, s57, s21
	s_mov_b32 m0, s61
	global_load_lds_dwordx4 v147, s[22:23]
	s_add_u32 s22, s54, s20
	s_addc_u32 s23, s55, s21
	s_add_i32 s63, s61, 0x400
	s_mov_b32 m0, s63
	global_load_lds_dwordx4 v148, s[22:23]
	s_add_u32 s22, s52, s20
	s_addc_u32 s23, s53, s21
	s_add_i32 s63, s61, 0x800
	s_mov_b32 m0, s63
	global_load_lds_dwordx4 v147, s[22:23]
	s_add_u32 s22, s50, s20
	s_addc_u32 s23, s51, s21
	s_add_i32 s63, s61, 0xc00
	s_mov_b32 m0, s63
	global_load_lds_dwordx4 v148, s[22:23]
	s_add_u32 s22, s48, s20
	s_addc_u32 s23, s49, s21
	s_mov_b32 m0, s62
	global_load_lds_dwordx4 v149, s[22:23]
	s_add_u32 s22, s46, s20
	s_addc_u32 s23, s47, s21
	s_add_i32 s62, s61, 0x8400
	s_mov_b32 m0, s62
	global_load_lds_dwordx4 v150, s[22:23]
	s_add_u32 s22, s44, s20
	s_addc_u32 s23, s45, s21
	s_add_i32 s62, s61, 0x8800
	s_mov_b32 m0, s62
	global_load_lds_dwordx4 v149, s[22:23]
	s_add_u32 s22, s25, s20
	s_addc_u32 s23, s43, s21
	s_add_i32 s61, s61, 0x8c00
	s_mov_b32 m0, s61
	global_load_lds_dwordx4 v150, s[22:23]
	s_branch .LBB0_326

.LBB0_397:
	s_waitcnt vmcnt(0)
	s_barrier
	s_and_b32 s10, s44, 0x10000
	v_or_b32_e32 v128, s10, v150
	v_add_u32_e32 v155, v128, v151
	ds_read_b128 v[130:133], v155 offset:32768
	ds_read_b128 v[160:163], v155 offset:36864
	v_add_u32_e32 v176, s10, v149
	v_add_u32_e32 v156, v176, v151
	ds_read_b128 v[134:137], v156
	ds_read_b128 v[138:141], v156 offset:4096
	ds_read_b128 v[142:145], v156 offset:8192
	v_add_u32_e32 v155, v176, v152
	ds_read_b128 v[156:159], v156 offset:12288
	s_add_i32 s45, s44, 0x10000
	s_cmp_lt_u32 s43, 15
	s_cbranch_scc0 .LBB0_396
	s_and_b32 s10, s45, 0x10000
	s_add_i32 s46, s10, s9
	s_add_i32 s47, s46, 0x8000
	s_add_u32 s10, s41, s4
	s_addc_u32 s11, s42, s5
	s_mov_b32 m0, s46
	global_load_lds_dwordx4 v147, s[10:11]
	s_add_u32 s10, s39, s4
	s_addc_u32 s11, s40, s5
	s_add_i32 s48, s46, 0x400
	s_mov_b32 m0, s48
	global_load_lds_dwordx4 v148, s[10:11]
	s_add_u32 s10, s37, s4
	s_addc_u32 s11, s38, s5
	s_add_i32 s48, s46, 0x800
	s_mov_b32 m0, s48
	global_load_lds_dwordx4 v147, s[10:11]
	s_add_u32 s10, s35, s4
	s_addc_u32 s11, s36, s5
	s_add_i32 s48, s46, 0xc00
	s_mov_b32 m0, s48
	global_load_lds_dwordx4 v148, s[10:11]
	s_add_u32 s10, s33, s4
	s_addc_u32 s11, s34, s5
	s_mov_b32 m0, s47
	global_load_lds_dwordx4 v147, s[10:11]
	s_add_u32 s10, s17, s4
	s_addc_u32 s11, s31, s5
	s_add_i32 s47, s46, 0x8400
	s_mov_b32 m0, s47
	global_load_lds_dwordx4 v148, s[10:11]
	s_add_u32 s10, s15, s4
	s_addc_u32 s11, s16, s5
	s_add_i32 s47, s46, 0x8800
	s_mov_b32 m0, s47
	global_load_lds_dwordx4 v147, s[10:11]
	s_add_u32 s10, s13, s4
	s_addc_u32 s11, s14, s5
	s_add_i32 s46, s46, 0x8c00
	s_mov_b32 m0, s46
	global_load_lds_dwordx4 v148, s[10:11]
	s_branch .LBB0_396

.LBB0_725:
	v_add_u32_e32 v162, v166, v189
	v_add_u32_e32 v167, v144, v189
	s_waitcnt lgkmcnt(2)
	v_mfma_f32_32x32x16_bf16 v[0:15], v[128:131], v[132:135], v[0:15]
	ds_read_b128 v[154:157], v162
	s_add_u32 s4, s4, 0x80
	s_addc_u32 s5, s5, 0
	s_add_i32 s45, s45, 1
	s_cmpk_lg_i32 s4, 0x800
	s_mov_b32 s46, s50
	v_mfma_f32_32x32x16_bf16 v[16:31], v[150:153], v[132:135], v[16:31]
	ds_read_b128 v[132:135], v162 offset:4096
	s_waitcnt lgkmcnt(4)
	v_mfma_f32_32x32x16_bf16 v[32:47], v[128:131], v[136:139], v[32:47]
	ds_read_b128 v[158:161], v162 offset:8192
	v_mfma_f32_32x32x16_bf16 v[48:63], v[150:153], v[136:139], v[48:63]
	ds_read_b128 v[136:139], v162 offset:12288
	s_waitcnt lgkmcnt(5)
	v_mfma_f32_32x32x16_bf16 v[64:79], v[128:131], v[140:143], v[64:79]
	ds_read_b128 v[162:165], v167 offset:32768
	v_mfma_f32_32x32x16_bf16 v[80:95], v[150:153], v[140:143], v[80:95]
	ds_read_b128 v[140:143], v167 offset:36864
	v_add_u32_e32 v167, v166, v190
	s_waitcnt lgkmcnt(6)
	v_mfma_f32_32x32x16_bf16 v[96:111], v[128:131], v[146:149], v[96:111]
	v_mfma_f32_32x32x16_bf16 v[112:127], v[150:153], v[146:149], v[112:127]
	s_waitcnt lgkmcnt(1)
	v_mfma_f32_32x32x16_bf16 v[0:15], v[162:165], v[154:157], v[0:15]
	ds_read_b128 v[128:131], v167
	s_waitcnt lgkmcnt(1)
	v_mfma_f32_32x32x16_bf16 v[16:31], v[140:143], v[154:157], v[16:31]
	ds_read_b128 v[146:149], v167 offset:4096
	v_mfma_f32_32x32x16_bf16 v[32:47], v[162:165], v[132:135], v[32:47]
	ds_read_b128 v[150:153], v167 offset:8192
	v_mfma_f32_32x32x16_bf16 v[48:63], v[140:143], v[132:135], v[48:63]
	ds_read_b128 v[132:135], v167 offset:12288
	v_add_u32_e32 v167, v144, v190
	v_add_u32_e32 v144, v144, v191
	v_mfma_f32_32x32x16_bf16 v[64:79], v[162:165], v[158:161], v[64:79]
	ds_read_b128 v[154:157], v167 offset:32768
	v_mfma_f32_32x32x16_bf16 v[80:95], v[140:143], v[158:161], v[80:95]
	ds_read_b128 v[158:161], v167 offset:36864
	v_mfma_f32_32x32x16_bf16 v[96:111], v[162:165], v[136:139], v[96:111]
	v_add_u32_e32 v162, v166, v191
	v_mfma_f32_32x32x16_bf16 v[112:127], v[140:143], v[136:139], v[112:127]
	s_waitcnt lgkmcnt(1)
	v_mfma_f32_32x32x16_bf16 v[0:15], v[154:157], v[128:131], v[0:15]
	ds_read_b128 v[136:139], v162
	s_waitcnt lgkmcnt(1)
	v_mfma_f32_32x32x16_bf16 v[16:31], v[158:161], v[128:131], v[16:31]
	ds_read_b128 v[128:131], v162 offset:4096
	v_mfma_f32_32x32x16_bf16 v[32:47], v[154:157], v[146:149], v[32:47]
	ds_read_b128 v[140:143], v162 offset:8192
	v_mfma_f32_32x32x16_bf16 v[48:63], v[158:161], v[146:149], v[48:63]
	ds_read_b128 v[146:149], v162 offset:12288
	v_mfma_f32_32x32x16_bf16 v[64:79], v[154:157], v[150:153], v[64:79]
	ds_read_b128 v[162:165], v144 offset:32768
	v_mfma_f32_32x32x16_bf16 v[80:95], v[158:161], v[150:153], v[80:95]
	ds_read_b128 v[150:153], v144 offset:36864
	v_mfma_f32_32x32x16_bf16 v[96:111], v[154:157], v[132:135], v[96:111]
	v_mfma_f32_32x32x16_bf16 v[112:127], v[158:161], v[132:135], v[112:127]
	s_waitcnt lgkmcnt(0)
	s_cbranch_scc0 .Lxt_L1
	s_waitcnt vmcnt(0)
	s_barrier
	s_and_b32 s6, s46, 0x10000
	v_or_b32_e32 v144, s6, v187
	v_add_u32_e32 v194, v144, v188
	v_add_u32_e32 v166, s6, v186
	v_add_u32_e32 v195, v166, v188
	ds_read_b128 v[132:135], v195
	v_mfma_f32_32x32x16_bf16 v[16:31], v[150:153], v[136:139], v[16:31]
	v_mfma_f32_32x32x16_bf16 v[48:63], v[150:153], v[128:131], v[48:63]
	v_mfma_f32_32x32x16_bf16 v[80:95], v[150:153], v[140:143], v[80:95]
	v_mfma_f32_32x32x16_bf16 v[112:127], v[150:153], v[146:149], v[112:127]
	ds_read_b128 v[150:153], v194 offset:36864
	v_mfma_f32_32x32x16_bf16 v[0:15], v[162:165], v[136:139], v[0:15]
	ds_read_b128 v[136:139], v195 offset:4096
	v_mfma_f32_32x32x16_bf16 v[32:47], v[162:165], v[128:131], v[32:47]
	ds_read_b128 v[128:131], v194 offset:32768
	v_mfma_f32_32x32x16_bf16 v[64:79], v[162:165], v[140:143], v[64:79]
	ds_read_b128 v[140:143], v195 offset:8192
	v_mfma_f32_32x32x16_bf16 v[96:111], v[162:165], v[146:149], v[96:111]
	ds_read_b128 v[146:149], v195 offset:12288
	s_add_i32 s50, s46, 0x10000
	s_cmp_lt_u32 s45, 15
	s_cbranch_scc0 .LBB0_725
	s_and_b32 s6, s50, 0x10000
	s_add_i32 s51, s6, s26
	s_add_i32 s52, s51, 0x8000
	s_add_u32 s82, s4, s81
	s_addk_i32 s82, 0x80
	s_and_b32 s82, s82, 0x7ff
	s_mov_b32 s83, 0
	s_add_u32 s6, s43, s82
	s_addc_u32 s7, s44, s83
	s_mov_b32 m0, s51
	global_load_lds_dwordx4 v177, s[6:7]
	s_add_u32 s6, s41, s82
	s_addc_u32 s7, s42, s83
	s_add_i32 s53, s51, 0x400
	s_mov_b32 m0, s53
	global_load_lds_dwordx4 v185, s[6:7]
	s_add_u32 s6, s39, s82
	s_addc_u32 s7, s40, s83
	s_add_i32 s53, s51, 0x800
	s_mov_b32 m0, s53
	global_load_lds_dwordx4 v177, s[6:7]
	s_add_u32 s6, s37, s82
	s_addc_u32 s7, s38, s83
	s_add_i32 s53, s51, 0xc00
	s_mov_b32 m0, s53
	global_load_lds_dwordx4 v185, s[6:7]
	s_add_u32 s6, s35, s82
	s_addc_u32 s7, s36, s83
	s_mov_b32 m0, s52
	global_load_lds_dwordx4 v177, s[6:7]
	s_add_u32 s6, s31, s82
	s_addc_u32 s7, s34, s83
	s_add_i32 s52, s51, 0x8400
	s_mov_b32 m0, s52
	global_load_lds_dwordx4 v185, s[6:7]
	s_add_u32 s6, s29, s82
	s_addc_u32 s7, s30, s83
	s_add_i32 s52, s51, 0x8800
	s_mov_b32 m0, s52
	global_load_lds_dwordx4 v177, s[6:7]
	s_add_u32 s6, s27, s82
	s_addc_u32 s7, s28, s83
	s_add_i32 s51, s51, 0x8c00
	s_mov_b32 m0, s51
	global_load_lds_dwordx4 v185, s[6:7]
	s_branch .LBB0_725

.Lkin_L1:
	s_and_b32 s6, s46, 0x10000
	v_or_b32_e32 v144, s6, v187
	v_add_u32_e32 v194, v144, v188
	v_add_u32_e32 v166, s6, v186
	v_add_u32_e32 v195, v166, v188
	ds_read_b128 v[132:135], v195
	ds_read_b128 v[150:153], v194 offset:36864
	ds_read_b128 v[136:139], v195 offset:4096
	ds_read_b128 v[128:131], v194 offset:32768
	ds_read_b128 v[140:143], v195 offset:8192
	ds_read_b128 v[146:149], v195 offset:12288
	s_add_i32 s50, s46, 0x10000
	s_cmp_lt_u32 s45, 15
	s_cbranch_scc0 .LBB0_725
	s_and_b32 s6, s50, 0x10000
	s_add_i32 s51, s6, s26
	s_add_i32 s52, s51, 0x8000
	s_add_u32 s82, s4, s81
	s_addk_i32 s82, 0x80
	s_and_b32 s82, s82, 0x7ff
	s_mov_b32 s83, 0
	s_add_u32 s6, s43, s82
	s_addc_u32 s7, s44, s83
	s_mov_b32 m0, s51
	global_load_lds_dwordx4 v177, s[6:7]
	s_add_u32 s6, s41, s82
	s_addc_u32 s7, s42, s83
	s_add_i32 s53, s51, 0x400
	s_mov_b32 m0, s53
	global_load_lds_dwordx4 v185, s[6:7]
	s_add_u32 s6, s39, s82
	s_addc_u32 s7, s40, s83
	s_add_i32 s53, s51, 0x800
	s_mov_b32 m0, s53
	global_load_lds_dwordx4 v177, s[6:7]
	s_add_u32 s6, s37, s82
	s_addc_u32 s7, s38, s83
	s_add_i32 s53, s51, 0xc00
	s_mov_b32 m0, s53
	global_load_lds_dwordx4 v185, s[6:7]
	s_add_u32 s6, s35, s82
	s_addc_u32 s7, s36, s83
	s_mov_b32 m0, s52
	global_load_lds_dwordx4 v177, s[6:7]
	s_add_u32 s6, s31, s82
	s_addc_u32 s7, s34, s83
	s_add_i32 s52, s51, 0x8400
	s_mov_b32 m0, s52
	global_load_lds_dwordx4 v185, s[6:7]
	s_add_u32 s6, s29, s82
	s_addc_u32 s7, s30, s83
	s_add_i32 s52, s51, 0x8800
	s_mov_b32 m0, s52
	global_load_lds_dwordx4 v177, s[6:7]
	s_add_u32 s6, s27, s82
	s_addc_u32 s7, s28, s83
	s_add_i32 s51, s51, 0x8c00
	s_mov_b32 m0, s51
	global_load_lds_dwordx4 v185, s[6:7]
	s_branch .LBB0_725

.LBB0_898:
	s_waitcnt vmcnt(0)
	s_barrier
	s_and_b32 s20, s57, 0x10000
	v_or_b32_e32 v128, s20, v152
	v_add_u32_e32 v157, v128, v153
	ds_read_b128 v[130:133], v157 offset:32768
	ds_read_b128 v[162:165], v157 offset:36864
	v_add_u32_e32 v180, s20, v151
	v_add_u32_e32 v158, v180, v153
	ds_read_b128 v[134:137], v158
	ds_read_b128 v[138:141], v158 offset:4096
	ds_read_b128 v[142:145], v158 offset:8192
	v_add_u32_e32 v157, v180, v154
	ds_read_b128 v[158:161], v158 offset:12288
	s_add_i32 s58, s57, 0x10000
	s_cmp_lt_u32 s56, 7
	s_cbranch_scc0 .LBB0_897
	s_and_b32 s20, s58, 0x10000
	s_add_i32 s59, s20, s23
	s_add_i32 s60, s59, 0x8000
	s_add_u32 s20, s54, s16
	s_addc_u32 s21, s55, s17
	s_mov_b32 m0, s59
	global_load_lds_dwordx4 v147, s[20:21]
	s_add_u32 s20, s52, s16
	s_addc_u32 s21, s53, s17
	s_add_i32 s61, s59, 0x400
	s_mov_b32 m0, s61
	global_load_lds_dwordx4 v148, s[20:21]
	s_add_u32 s20, s50, s16
	s_addc_u32 s21, s51, s17
	s_add_i32 s61, s59, 0x800
	s_mov_b32 m0, s61
	global_load_lds_dwordx4 v147, s[20:21]
	s_add_u32 s20, s48, s16
	s_addc_u32 s21, s49, s17
	s_add_i32 s61, s59, 0xc00
	s_mov_b32 m0, s61
	global_load_lds_dwordx4 v148, s[20:21]
	s_add_u32 s20, s46, s16
	s_addc_u32 s21, s47, s17
	s_mov_b32 m0, s60
	global_load_lds_dwordx4 v149, s[20:21]
	s_add_u32 s20, s44, s16
	s_addc_u32 s21, s45, s17
	s_add_i32 s60, s59, 0x8400
	s_mov_b32 m0, s60
	global_load_lds_dwordx4 v150, s[20:21]
	s_add_u32 s20, s41, s16
	s_addc_u32 s21, s43, s17
	s_add_i32 s60, s59, 0x8800
	s_mov_b32 m0, s60
	global_load_lds_dwordx4 v149, s[20:21]
	s_add_u32 s20, s33, s16
	s_addc_u32 s21, s40, s17
	s_add_i32 s59, s59, 0x8c00
	s_mov_b32 m0, s59
	global_load_lds_dwordx4 v150, s[20:21]
	s_branch .LBB0_897

.LBB0_912:
	s_waitcnt vmcnt(0)
	s_barrier
	s_and_b32 s20, s57, 0x10000
	v_or_b32_e32 v128, s20, v152
	v_add_u32_e32 v157, v128, v153
	ds_read_b128 v[130:133], v157 offset:32768
	ds_read_b128 v[162:165], v157 offset:36864
	v_add_u32_e32 v180, s20, v151
	v_add_u32_e32 v158, v180, v153
	ds_read_b128 v[134:137], v158
	ds_read_b128 v[138:141], v158 offset:4096
	ds_read_b128 v[142:145], v158 offset:8192
	v_add_u32_e32 v157, v180, v154
	ds_read_b128 v[158:161], v158 offset:12288
	s_add_i32 s58, s57, 0x10000
	s_cmp_lt_u32 s56, 7
	s_cbranch_scc0 .LBB0_911
	s_and_b32 s20, s58, 0x10000
	s_add_i32 s59, s20, s22
	s_add_i32 s60, s59, 0x8000
	s_add_u32 s20, s54, s18
	s_addc_u32 s21, s55, s19
	s_mov_b32 m0, s59
	global_load_lds_dwordx4 v147, s[20:21]
	s_add_u32 s20, s52, s18
	s_addc_u32 s21, s53, s19
	s_add_i32 s61, s59, 0x400
	s_mov_b32 m0, s61
	global_load_lds_dwordx4 v148, s[20:21]
	s_add_u32 s20, s50, s18
	s_addc_u32 s21, s51, s19
	s_add_i32 s61, s59, 0x800
	s_mov_b32 m0, s61
	global_load_lds_dwordx4 v147, s[20:21]
	s_add_u32 s20, s48, s18
	s_addc_u32 s21, s49, s19
	s_add_i32 s61, s59, 0xc00
	s_mov_b32 m0, s61
	global_load_lds_dwordx4 v148, s[20:21]
	s_add_u32 s20, s46, s18
	s_addc_u32 s21, s47, s19
	s_mov_b32 m0, s60
	global_load_lds_dwordx4 v149, s[20:21]
	s_add_u32 s20, s44, s18
	s_addc_u32 s21, s45, s19
	s_add_i32 s60, s59, 0x8400
	s_mov_b32 m0, s60
	global_load_lds_dwordx4 v150, s[20:21]
	s_add_u32 s20, s42, s18
	s_addc_u32 s21, s43, s19
	s_add_i32 s60, s59, 0x8800
	s_mov_b32 m0, s60
	global_load_lds_dwordx4 v149, s[20:21]
	s_add_u32 s20, s23, s18
	s_addc_u32 s21, s33, s19
	s_add_i32 s59, s59, 0x8c00
	s_mov_b32 m0, s59
	global_load_lds_dwordx4 v150, s[20:21]
	s_branch .LBB0_911

.LBB0_982:
	s_waitcnt vmcnt(0)
	s_barrier
	s_and_b32 s10, s44, 0x10000
	v_or_b32_e32 v128, s10, v148
	v_add_u32_e32 v142, v128, v149
	ds_read_b128 v[130:133], v142 offset:32768
	ds_read_b128 v[162:165], v142 offset:36864
	v_add_u32_e32 v143, s10, v147
	v_add_u32_e32 v153, v143, v149
	ds_read_b128 v[134:137], v153
	ds_read_b128 v[138:141], v153 offset:4096
	ds_read_b128 v[154:157], v153 offset:8192
	v_add_u32_e32 v142, v143, v150
	ds_read_b128 v[158:161], v153 offset:12288
	s_add_i32 s45, s44, 0x10000
	s_cmp_lt_u32 s43, 15
	s_cbranch_scc0 .LBB0_981
	s_and_b32 s10, s45, 0x10000
	s_add_i32 s46, s10, s9
	s_add_i32 s47, s46, 0x8000
	s_add_u32 s10, s41, s0
	s_addc_u32 s11, s42, s1
	s_mov_b32 m0, s46
	global_load_lds_dwordx4 v145, s[10:11]
	s_add_u32 s10, s39, s0
	s_addc_u32 s11, s40, s1
	s_add_i32 s48, s46, 0x400
	s_mov_b32 m0, s48
	global_load_lds_dwordx4 v146, s[10:11]
	s_add_u32 s10, s37, s0
	s_addc_u32 s11, s38, s1
	s_add_i32 s48, s46, 0x800
	s_mov_b32 m0, s48
	global_load_lds_dwordx4 v145, s[10:11]
	s_add_u32 s10, s35, s0
	s_addc_u32 s11, s36, s1
	s_add_i32 s48, s46, 0xc00
	s_mov_b32 m0, s48
	global_load_lds_dwordx4 v146, s[10:11]
	s_add_u32 s10, s33, s0
	s_addc_u32 s11, s34, s1
	s_mov_b32 m0, s47
	global_load_lds_dwordx4 v145, s[10:11]
	s_add_u32 s10, s17, s0
	s_addc_u32 s11, s31, s1
	s_add_i32 s47, s46, 0x8400
	s_mov_b32 m0, s47
	global_load_lds_dwordx4 v146, s[10:11]
	s_add_u32 s10, s15, s0
	s_addc_u32 s11, s16, s1
	s_add_i32 s47, s46, 0x8800
	s_mov_b32 m0, s47
	global_load_lds_dwordx4 v145, s[10:11]
	s_add_u32 s10, s13, s0
	s_addc_u32 s11, s14, s1
	s_add_i32 s46, s46, 0x8c00
	s_mov_b32 m0, s46
	global_load_lds_dwordx4 v146, s[10:11]
	s_branch .LBB0_981
